# GEMM units: first K-loop trip peeled with C = 0 on each accumulator's first MFMA, the 128 clearing moves per unit removed
# speedup vs baseline: 1.0129x; 1.0061x over previous
.LBB0_205:
	s_ashr_i32 s55, s54, 31
	s_lshl_b64 s[56:57], s[54:55], 19
	s_add_u32 s56, s65, s56
	s_addc_u32 s57, s66, s57
	s_and_b64 s[58:59], s[38:39], exec
	s_cselect_b32 s9, s57, s23
	s_cselect_b32 s31, s56, s22
	s_ashr_i32 s53, s52, 31
	s_lshl_b64 s[58:59], s[52:53], 19
	s_add_u32 s58, s63, s58
	s_addc_u32 s59, s64, s59
	s_and_b64 s[60:61], s[38:39], exec
	s_cselect_b32 s41, s59, s43
	s_cselect_b32 s53, s58, s42
	s_add_u32 s22, s22, 0x40080
	s_addc_u32 s23, s23, 0
	s_add_u32 s55, s42, 0x100
	s_addc_u32 vcc_lo, s43, 0
	s_mov_b32 vcc_hi, -2
	s_add_u32 s10, s22, 0xfffc0080
	s_addc_u32 s11, s23, -1
	s_add_i32 s12, 0, 0x10000
	s_cmp_eq_u32 vcc_hi, 12
	s_cselect_b32 s61, s9, s11
	s_cselect_b32 s60, s31, s10
	v_add_u32_e32 v152, s12, v157
	s_cselect_b32 s43, s41, vcc_lo
	s_cselect_b32 s42, s53, s55
	s_add_i32 s13, 0, 0x14000
	ds_read_b128 v[140:143], v152
	ds_read_b128 v[144:147], v152 offset:1024
	ds_read_b128 v[148:151], v152 offset:2048
	ds_read_b128 v[160:163], v152 offset:3072
	v_add_u32_e32 v152, s13, v157
	ds_read_b128 v[164:167], v152
	ds_read_b128 v[168:171], v152 offset:1024
	ds_read_b128 v[172:175], v152 offset:2048
	ds_read_b128 v[176:179], v152 offset:3072
	s_add_u32 s10, s22, 0xfffc0000
	s_addc_u32 s11, s23, -1
	s_mov_b32 m0, s83
	s_nop 0
	global_load_lds_dwordx4 v136, s[10:11]
	s_mov_b32 m0, s95
	s_nop 0
	global_load_lds_dwordx4 v138, s[10:11]
	s_add_i32 m0, s75, 0xc000
	ds_read_b128 v[180:183], v159
	ds_read_b128 v[184:187], v159 offset:1024
	ds_read_b128 v[188:191], v159 offset:2048
	ds_read_b128 v[206:209], v159 offset:3072
	ds_read_b128 v[210:213], v159 offset:4096
	ds_read_b128 v[214:217], v159 offset:5120
	ds_read_b128 v[218:221], v159 offset:6144
	ds_read_b128 v[222:225], v159 offset:7168
	global_load_lds_dwordx4 v136, s[22:23]
	s_add_i32 m0, s75, 0xe000
	s_nop 0
	global_load_lds_dwordx4 v138, s[22:23]
	s_waitcnt vmcnt(8)
	s_waitcnt lgkmcnt(0)
	s_barrier
	s_setprio 1
	s_waitcnt lgkmcnt(0)
	v_mfma_f32_16x16x32_bf16 v[124:127], v[140:143], v[180:183], 0
	v_mfma_f32_16x16x32_bf16 v[120:123], v[148:151], v[180:183], 0
	v_mfma_f32_16x16x32_bf16 v[108:111], v[140:143], v[188:191], 0
	v_mfma_f32_16x16x32_bf16 v[104:107], v[148:151], v[188:191], 0
	v_mfma_f32_16x16x32_bf16 v[92:95], v[140:143], v[210:213], 0
	v_mfma_f32_16x16x32_bf16 v[88:91], v[148:151], v[210:213], 0
	v_mfma_f32_16x16x32_bf16 v[76:79], v[140:143], v[218:221], 0
	v_mfma_f32_16x16x32_bf16 v[72:75], v[148:151], v[218:221], 0
	v_mfma_f32_16x16x32_bf16 v[124:127], v[144:147], v[184:187], v[124:127]
	v_mfma_f32_16x16x32_bf16 v[120:123], v[160:163], v[184:187], v[120:123]
	v_mfma_f32_16x16x32_bf16 v[108:111], v[144:147], v[206:209], v[108:111]
	v_mfma_f32_16x16x32_bf16 v[104:107], v[160:163], v[206:209], v[104:107]
	v_mfma_f32_16x16x32_bf16 v[92:95], v[144:147], v[214:217], v[92:95]
	v_mfma_f32_16x16x32_bf16 v[88:91], v[160:163], v[214:217], v[88:91]
	v_mfma_f32_16x16x32_bf16 v[76:79], v[144:147], v[222:225], v[76:79]
	v_mfma_f32_16x16x32_bf16 v[72:75], v[160:163], v[222:225], v[72:75]
	s_setprio 0
	s_setprio 1
	v_mfma_f32_16x16x32_bf16 v[116:119], v[164:167], v[180:183], 0
	v_mfma_f32_16x16x32_bf16 v[112:115], v[172:175], v[180:183], 0
	v_mfma_f32_16x16x32_bf16 v[100:103], v[164:167], v[188:191], 0
	v_mfma_f32_16x16x32_bf16 v[96:99], v[172:175], v[188:191], 0
	v_mfma_f32_16x16x32_bf16 v[84:87], v[164:167], v[210:213], 0
	v_mfma_f32_16x16x32_bf16 v[80:83], v[172:175], v[210:213], 0
	v_mfma_f32_16x16x32_bf16 v[68:71], v[164:167], v[218:221], 0
	v_mfma_f32_16x16x32_bf16 v[64:67], v[172:175], v[218:221], 0
	v_mfma_f32_16x16x32_bf16 v[116:119], v[168:171], v[184:187], v[116:119]
	v_mfma_f32_16x16x32_bf16 v[112:115], v[176:179], v[184:187], v[112:115]
	v_mfma_f32_16x16x32_bf16 v[100:103], v[168:171], v[206:209], v[100:103]
	v_mfma_f32_16x16x32_bf16 v[96:99], v[176:179], v[206:209], v[96:99]
	v_mfma_f32_16x16x32_bf16 v[84:87], v[168:171], v[214:217], v[84:87]
	v_mfma_f32_16x16x32_bf16 v[80:83], v[176:179], v[214:217], v[80:83]
	v_mfma_f32_16x16x32_bf16 v[68:71], v[168:171], v[222:225], v[68:71]
	v_mfma_f32_16x16x32_bf16 v[64:67], v[176:179], v[222:225], v[64:67]
	s_setprio 0
	s_barrier
	s_add_i32 s10, s12, s67
	s_mov_b32 m0, s10
	ds_read_b128 v[180:183], v159 offset:16384
	ds_read_b128 v[184:187], v159 offset:17408
	ds_read_b128 v[188:191], v159 offset:18432
	ds_read_b128 v[206:209], v159 offset:19456
	ds_read_b128 v[210:213], v159 offset:20480
	ds_read_b128 v[214:217], v159 offset:21504
	ds_read_b128 v[218:221], v159 offset:22528
	ds_read_b128 v[222:225], v159 offset:23552
	global_load_lds_dwordx4 v192, s[42:43]
	s_add_i32 m0, s10, 0x2000
	s_add_u32 s10, s42, 0x40000
	s_addc_u32 s11, s43, 0
	s_add_i32 s12, s13, s67
	global_load_lds_dwordx4 v132, s[42:43]
	s_mov_b32 m0, s12
	s_nop 0
	global_load_lds_dwordx4 v192, s[10:11]
	s_add_i32 m0, s12, 0x2000
	s_nop 0
	global_load_lds_dwordx4 v132, s[10:11]
	s_waitcnt vmcnt(6)
	s_waitcnt lgkmcnt(0)
	s_barrier
	s_setprio 1
	s_waitcnt lgkmcnt(0)
	v_mfma_f32_16x16x32_bf16 v[60:63], v[140:143], v[180:183], 0
	v_mfma_f32_16x16x32_bf16 v[56:59], v[148:151], v[180:183], 0
	v_mfma_f32_16x16x32_bf16 v[44:47], v[140:143], v[188:191], 0
	v_mfma_f32_16x16x32_bf16 v[40:43], v[148:151], v[188:191], 0
	v_mfma_f32_16x16x32_bf16 v[28:31], v[140:143], v[210:213], 0
	v_mfma_f32_16x16x32_bf16 v[24:27], v[148:151], v[210:213], 0
	v_mfma_f32_16x16x32_bf16 v[12:15], v[140:143], v[218:221], 0
	v_mfma_f32_16x16x32_bf16 v[8:11], v[148:151], v[218:221], 0
	v_mfma_f32_16x16x32_bf16 v[60:63], v[144:147], v[184:187], v[60:63]
	v_mfma_f32_16x16x32_bf16 v[56:59], v[160:163], v[184:187], v[56:59]
	v_mfma_f32_16x16x32_bf16 v[44:47], v[144:147], v[206:209], v[44:47]
	v_mfma_f32_16x16x32_bf16 v[40:43], v[160:163], v[206:209], v[40:43]
	v_mfma_f32_16x16x32_bf16 v[28:31], v[144:147], v[214:217], v[28:31]
	v_mfma_f32_16x16x32_bf16 v[24:27], v[160:163], v[214:217], v[24:27]
	v_mfma_f32_16x16x32_bf16 v[12:15], v[144:147], v[222:225], v[12:15]
	v_mfma_f32_16x16x32_bf16 v[8:11], v[160:163], v[222:225], v[8:11]
	s_setprio 0
	s_setprio 1
	v_mfma_f32_16x16x32_bf16 v[52:55], v[164:167], v[180:183], 0
	v_mfma_f32_16x16x32_bf16 v[48:51], v[172:175], v[180:183], 0
	v_mfma_f32_16x16x32_bf16 v[36:39], v[164:167], v[188:191], 0
	v_mfma_f32_16x16x32_bf16 v[32:35], v[172:175], v[188:191], 0
	v_mfma_f32_16x16x32_bf16 v[20:23], v[164:167], v[210:213], 0
	v_mfma_f32_16x16x32_bf16 v[16:19], v[172:175], v[210:213], 0
	v_mfma_f32_16x16x32_bf16 v[4:7], v[164:167], v[218:221], 0
	v_mfma_f32_16x16x32_bf16 v[0:3], v[172:175], v[218:221], 0
	v_mfma_f32_16x16x32_bf16 v[52:55], v[168:171], v[184:187], v[52:55]
	v_mfma_f32_16x16x32_bf16 v[48:51], v[176:179], v[184:187], v[48:51]
	v_mfma_f32_16x16x32_bf16 v[36:39], v[168:171], v[206:209], v[36:39]
	v_mfma_f32_16x16x32_bf16 v[32:35], v[176:179], v[206:209], v[32:35]
	v_mfma_f32_16x16x32_bf16 v[20:23], v[168:171], v[214:217], v[20:23]
	v_mfma_f32_16x16x32_bf16 v[16:19], v[176:179], v[214:217], v[16:19]
	v_mfma_f32_16x16x32_bf16 v[4:7], v[168:171], v[222:225], v[4:7]
	v_mfma_f32_16x16x32_bf16 v[0:3], v[176:179], v[222:225], v[0:3]
	s_setprio 0
	s_barrier
	s_add_i32 s12, 0, 0x18000
	s_add_i32 s13, 0, 0x1c000
	v_add_u32_e32 v160, s12, v157
	v_add_u32_e32 v176, s13, v157
	ds_read_b128 v[140:143], v160
	ds_read_b128 v[144:147], v160 offset:1024
	ds_read_b128 v[148:151], v160 offset:2048
	ds_read_b128 v[160:163], v160 offset:3072
	ds_read_b128 v[164:167], v176
	ds_read_b128 v[168:171], v176 offset:1024
	ds_read_b128 v[172:175], v176 offset:2048
	ds_read_b128 v[176:179], v176 offset:3072
	s_mov_b32 m0, s75
	s_nop 0
	global_load_lds_dwordx4 v128, s[60:61]
	s_mov_b32 m0, s78
	s_nop 0
	global_load_lds_dwordx4 v130, s[60:61]
	s_add_u32 s10, s60, 0x40000
	s_addc_u32 s11, s61, 0
	s_mov_b32 m0, s79
	ds_read_b128 v[180:183], v159 offset:32768
	ds_read_b128 v[184:187], v159 offset:33792
	ds_read_b128 v[188:191], v159 offset:34816
	ds_read_b128 v[206:209], v159 offset:35840
	ds_read_b128 v[210:213], v159 offset:36864
	ds_read_b128 v[214:217], v159 offset:37888
	ds_read_b128 v[218:221], v159 offset:38912
	ds_read_b128 v[222:225], v159 offset:39936
	global_load_lds_dwordx4 v128, s[10:11]
	s_mov_b32 m0, s82
	s_nop 0
	global_load_lds_dwordx4 v130, s[10:11]
	s_waitcnt vmcnt(8)
	s_waitcnt lgkmcnt(0)
	s_barrier
	s_setprio 1
	s_waitcnt lgkmcnt(0)
	v_mfma_f32_16x16x32_bf16 v[124:127], v[140:143], v[180:183], v[124:127]
	v_mfma_f32_16x16x32_bf16 v[120:123], v[148:151], v[180:183], v[120:123]
	v_mfma_f32_16x16x32_bf16 v[108:111], v[140:143], v[188:191], v[108:111]
	v_mfma_f32_16x16x32_bf16 v[104:107], v[148:151], v[188:191], v[104:107]
	v_mfma_f32_16x16x32_bf16 v[92:95], v[140:143], v[210:213], v[92:95]
	v_mfma_f32_16x16x32_bf16 v[88:91], v[148:151], v[210:213], v[88:91]
	v_mfma_f32_16x16x32_bf16 v[76:79], v[140:143], v[218:221], v[76:79]
	v_mfma_f32_16x16x32_bf16 v[72:75], v[148:151], v[218:221], v[72:75]
	v_mfma_f32_16x16x32_bf16 v[124:127], v[144:147], v[184:187], v[124:127]
	v_mfma_f32_16x16x32_bf16 v[120:123], v[160:163], v[184:187], v[120:123]
	v_mfma_f32_16x16x32_bf16 v[108:111], v[144:147], v[206:209], v[108:111]
	v_mfma_f32_16x16x32_bf16 v[104:107], v[160:163], v[206:209], v[104:107]
	v_mfma_f32_16x16x32_bf16 v[92:95], v[144:147], v[214:217], v[92:95]
	v_mfma_f32_16x16x32_bf16 v[88:91], v[160:163], v[214:217], v[88:91]
	v_mfma_f32_16x16x32_bf16 v[76:79], v[144:147], v[222:225], v[76:79]
	v_mfma_f32_16x16x32_bf16 v[72:75], v[160:163], v[222:225], v[72:75]
	s_setprio 0
	s_setprio 1
	v_mfma_f32_16x16x32_bf16 v[116:119], v[164:167], v[180:183], v[116:119]
	v_mfma_f32_16x16x32_bf16 v[112:115], v[172:175], v[180:183], v[112:115]
	v_mfma_f32_16x16x32_bf16 v[100:103], v[164:167], v[188:191], v[100:103]
	v_mfma_f32_16x16x32_bf16 v[96:99], v[172:175], v[188:191], v[96:99]
	v_mfma_f32_16x16x32_bf16 v[84:87], v[164:167], v[210:213], v[84:87]
	v_mfma_f32_16x16x32_bf16 v[80:83], v[172:175], v[210:213], v[80:83]
	v_mfma_f32_16x16x32_bf16 v[68:71], v[164:167], v[218:221], v[68:71]
	v_mfma_f32_16x16x32_bf16 v[64:67], v[172:175], v[218:221], v[64:67]
	v_mfma_f32_16x16x32_bf16 v[116:119], v[168:171], v[184:187], v[116:119]
	v_mfma_f32_16x16x32_bf16 v[112:115], v[176:179], v[184:187], v[112:115]
	v_mfma_f32_16x16x32_bf16 v[100:103], v[168:171], v[206:209], v[100:103]
	v_mfma_f32_16x16x32_bf16 v[96:99], v[176:179], v[206:209], v[96:99]
	v_mfma_f32_16x16x32_bf16 v[84:87], v[168:171], v[214:217], v[84:87]
	v_mfma_f32_16x16x32_bf16 v[80:83], v[176:179], v[214:217], v[80:83]
	v_mfma_f32_16x16x32_bf16 v[68:71], v[168:171], v[222:225], v[68:71]
	v_mfma_f32_16x16x32_bf16 v[64:67], v[176:179], v[222:225], v[64:67]
	s_setprio 0
	s_barrier
	s_add_i32 s10, s12, s67
	s_add_i32 m0, s10, 0xffffff80
	ds_read_b128 v[180:183], v159 offset:49152
	ds_read_b128 v[184:187], v159 offset:50176
	ds_read_b128 v[188:191], v159 offset:51200
	ds_read_b128 v[206:209], v159 offset:52224
	ds_read_b128 v[210:213], v159 offset:53248
	ds_read_b128 v[214:217], v159 offset:54272
	ds_read_b128 v[218:221], v159 offset:55296
	ds_read_b128 v[222:225], v159 offset:56320
	global_load_lds_dwordx4 v192, s[42:43] offset:128
	s_add_i32 m0, s10, 0x1f80
	s_add_u32 s10, s42, 0x40080
	s_addc_u32 s11, s43, 0
	s_add_i32 s12, s13, s67
	global_load_lds_dwordx4 v132, s[42:43] offset:128
	s_mov_b32 m0, s12
	s_nop 0
	global_load_lds_dwordx4 v192, s[10:11]
	s_add_i32 m0, s12, 0x2000
	s_nop 0
	global_load_lds_dwordx4 v132, s[10:11]
	s_waitcnt vmcnt(6)
	s_waitcnt lgkmcnt(0)
	s_barrier
	s_setprio 1
	s_waitcnt lgkmcnt(0)
	v_mfma_f32_16x16x32_bf16 v[60:63], v[140:143], v[180:183], v[60:63]
	v_mfma_f32_16x16x32_bf16 v[56:59], v[148:151], v[180:183], v[56:59]
	v_mfma_f32_16x16x32_bf16 v[44:47], v[140:143], v[188:191], v[44:47]
	v_mfma_f32_16x16x32_bf16 v[40:43], v[148:151], v[188:191], v[40:43]
	v_mfma_f32_16x16x32_bf16 v[28:31], v[140:143], v[210:213], v[28:31]
	v_mfma_f32_16x16x32_bf16 v[24:27], v[148:151], v[210:213], v[24:27]
	v_mfma_f32_16x16x32_bf16 v[12:15], v[140:143], v[218:221], v[12:15]
	v_mfma_f32_16x16x32_bf16 v[8:11], v[148:151], v[218:221], v[8:11]
	v_mfma_f32_16x16x32_bf16 v[60:63], v[144:147], v[184:187], v[60:63]
	v_mfma_f32_16x16x32_bf16 v[56:59], v[160:163], v[184:187], v[56:59]
	v_mfma_f32_16x16x32_bf16 v[44:47], v[144:147], v[206:209], v[44:47]
	v_mfma_f32_16x16x32_bf16 v[40:43], v[160:163], v[206:209], v[40:43]
	v_mfma_f32_16x16x32_bf16 v[28:31], v[144:147], v[214:217], v[28:31]
	v_mfma_f32_16x16x32_bf16 v[24:27], v[160:163], v[214:217], v[24:27]
	v_mfma_f32_16x16x32_bf16 v[12:15], v[144:147], v[222:225], v[12:15]
	v_mfma_f32_16x16x32_bf16 v[8:11], v[160:163], v[222:225], v[8:11]
	s_setprio 0
	s_setprio 1
	v_mfma_f32_16x16x32_bf16 v[52:55], v[164:167], v[180:183], v[52:55]
	v_mfma_f32_16x16x32_bf16 v[48:51], v[172:175], v[180:183], v[48:51]
	v_mfma_f32_16x16x32_bf16 v[36:39], v[164:167], v[188:191], v[36:39]
	v_mfma_f32_16x16x32_bf16 v[32:35], v[172:175], v[188:191], v[32:35]
	v_mfma_f32_16x16x32_bf16 v[20:23], v[164:167], v[210:213], v[20:23]
	v_mfma_f32_16x16x32_bf16 v[16:19], v[172:175], v[210:213], v[16:19]
	v_mfma_f32_16x16x32_bf16 v[4:7], v[164:167], v[218:221], v[4:7]
	v_mfma_f32_16x16x32_bf16 v[0:3], v[172:175], v[218:221], v[0:3]
	v_mfma_f32_16x16x32_bf16 v[52:55], v[168:171], v[184:187], v[52:55]
	v_mfma_f32_16x16x32_bf16 v[48:51], v[176:179], v[184:187], v[48:51]
	v_mfma_f32_16x16x32_bf16 v[36:39], v[168:171], v[206:209], v[36:39]
	v_mfma_f32_16x16x32_bf16 v[32:35], v[176:179], v[206:209], v[32:35]
	v_mfma_f32_16x16x32_bf16 v[20:23], v[168:171], v[214:217], v[20:23]
	v_mfma_f32_16x16x32_bf16 v[16:19], v[176:179], v[214:217], v[16:19]
	v_mfma_f32_16x16x32_bf16 v[4:7], v[168:171], v[222:225], v[4:7]
	v_mfma_f32_16x16x32_bf16 v[0:3], v[176:179], v[222:225], v[0:3]
	s_setprio 0
	s_barrier
	s_add_i32 vcc_hi, vcc_hi, 2
	s_add_u32 s22, s22, 0x100
	s_addc_u32 s23, s23, 0
	s_add_u32 s55, s55, 0x100
	s_addc_u32 vcc_lo, vcc_lo, 0
	s_cmp_gt_u32 vcc_hi, 13

.LBB0_1038:
	s_ashr_i32 s51, s50, 31
	s_lshl_b64 s[10:11], s[50:51], 19
	s_add_u32 s52, s22, s10
	s_addc_u32 s53, s23, s11
	s_and_b64 s[10:11], s[40:41], exec
	s_cselect_b32 s51, s53, s61
	s_cselect_b32 s57, s52, s60
	s_ashr_i32 s49, s48, 31
	s_lshl_b64 s[10:11], s[48:49], 19
	s_add_u32 s54, s5, s10
	s_addc_u32 s55, s6, s11
	s_and_b64 s[10:11], s[40:41], exec
	s_cselect_b32 s49, s55, s63
	s_cselect_b32 s82, s54, s62
	s_add_u32 s60, s60, 0x40080
	s_addc_u32 s61, s61, 0
	s_add_u32 s83, s62, 0x100
	s_addc_u32 s95, s63, 0
	s_mov_b32 s96, -2
	s_waitcnt lgkmcnt(0)
	s_add_u32 s10, s60, 0xfffc0080
	s_addc_u32 s11, s61, -1
	s_add_i32 s12, 0, 0x10000
	s_cmp_eq_u32 s96, 12
	s_cselect_b32 s65, s51, s11
	s_cselect_b32 s64, s57, s10
	v_add_u32_e32 v142, s12, v147
	s_cselect_b32 s63, s49, s95
	s_cselect_b32 s62, s82, s83
	s_add_i32 s13, 0, 0x14000
	ds_read_b128 v[138:141], v142
	ds_read_b128 v[150:153], v142 offset:1024
	ds_read_b128 v[154:157], v142 offset:2048
	ds_read_b128 v[158:161], v142 offset:3072
	v_add_u32_e32 v142, s13, v147
	ds_read_b128 v[162:165], v142
	ds_read_b128 v[166:169], v142 offset:1024
	ds_read_b128 v[170:173], v142 offset:2048
	ds_read_b128 v[174:177], v142 offset:3072
	s_add_u32 s10, s60, 0xfffc0000
	s_addc_u32 s11, s61, -1
	s_mov_b32 m0, s66
	s_nop 0
	global_load_lds_dwordx4 v134, s[10:11]
	s_mov_b32 m0, s67
	s_nop 0
	global_load_lds_dwordx4 v136, s[10:11]
	s_add_i32 m0, s8, 0xc000
	ds_read_b128 v[178:181], v149
	ds_read_b128 v[182:185], v149 offset:1024
	ds_read_b128 v[186:189], v149 offset:2048
	ds_read_b128 v[206:209], v149 offset:3072
	ds_read_b128 v[210:213], v149 offset:4096
	ds_read_b128 v[214:217], v149 offset:5120
	ds_read_b128 v[218:221], v149 offset:6144
	ds_read_b128 v[222:225], v149 offset:7168
	global_load_lds_dwordx4 v134, s[60:61]
	s_add_i32 m0, s8, 0xe000
	s_nop 0
	global_load_lds_dwordx4 v136, s[60:61]
	s_waitcnt vmcnt(8)
	s_waitcnt lgkmcnt(0)
	s_barrier
	s_setprio 1
	s_waitcnt lgkmcnt(0)
	v_mfma_f32_16x16x32_bf16 v[124:127], v[138:141], v[178:181], 0
	v_mfma_f32_16x16x32_bf16 v[120:123], v[154:157], v[178:181], 0
	v_mfma_f32_16x16x32_bf16 v[108:111], v[138:141], v[186:189], 0
	v_mfma_f32_16x16x32_bf16 v[104:107], v[154:157], v[186:189], 0
	v_mfma_f32_16x16x32_bf16 v[92:95], v[138:141], v[210:213], 0
	v_mfma_f32_16x16x32_bf16 v[88:91], v[154:157], v[210:213], 0
	v_mfma_f32_16x16x32_bf16 v[76:79], v[138:141], v[218:221], 0
	v_mfma_f32_16x16x32_bf16 v[72:75], v[154:157], v[218:221], 0
	v_mfma_f32_16x16x32_bf16 v[124:127], v[150:153], v[182:185], v[124:127]
	v_mfma_f32_16x16x32_bf16 v[120:123], v[158:161], v[182:185], v[120:123]
	v_mfma_f32_16x16x32_bf16 v[108:111], v[150:153], v[206:209], v[108:111]
	v_mfma_f32_16x16x32_bf16 v[104:107], v[158:161], v[206:209], v[104:107]
	v_mfma_f32_16x16x32_bf16 v[92:95], v[150:153], v[214:217], v[92:95]
	v_mfma_f32_16x16x32_bf16 v[88:91], v[158:161], v[214:217], v[88:91]
	v_mfma_f32_16x16x32_bf16 v[76:79], v[150:153], v[222:225], v[76:79]
	v_mfma_f32_16x16x32_bf16 v[72:75], v[158:161], v[222:225], v[72:75]
	s_setprio 0
	s_setprio 1
	v_mfma_f32_16x16x32_bf16 v[116:119], v[162:165], v[178:181], 0
	v_mfma_f32_16x16x32_bf16 v[112:115], v[170:173], v[178:181], 0
	v_mfma_f32_16x16x32_bf16 v[100:103], v[162:165], v[186:189], 0
	v_mfma_f32_16x16x32_bf16 v[96:99], v[170:173], v[186:189], 0
	v_mfma_f32_16x16x32_bf16 v[84:87], v[162:165], v[210:213], 0
	v_mfma_f32_16x16x32_bf16 v[80:83], v[170:173], v[210:213], 0
	v_mfma_f32_16x16x32_bf16 v[68:71], v[162:165], v[218:221], 0
	v_mfma_f32_16x16x32_bf16 v[64:67], v[170:173], v[218:221], 0
	v_mfma_f32_16x16x32_bf16 v[116:119], v[166:169], v[182:185], v[116:119]
	v_mfma_f32_16x16x32_bf16 v[112:115], v[174:177], v[182:185], v[112:115]
	v_mfma_f32_16x16x32_bf16 v[100:103], v[166:169], v[206:209], v[100:103]
	v_mfma_f32_16x16x32_bf16 v[96:99], v[174:177], v[206:209], v[96:99]
	v_mfma_f32_16x16x32_bf16 v[84:87], v[166:169], v[214:217], v[84:87]
	v_mfma_f32_16x16x32_bf16 v[80:83], v[174:177], v[214:217], v[80:83]
	v_mfma_f32_16x16x32_bf16 v[68:71], v[166:169], v[222:225], v[68:71]
	v_mfma_f32_16x16x32_bf16 v[64:67], v[174:177], v[222:225], v[64:67]
	s_setprio 0
	s_barrier
	s_add_i32 s10, s12, s7
	s_mov_b32 m0, s10
	ds_read_b128 v[178:181], v149 offset:16384
	ds_read_b128 v[182:185], v149 offset:17408
	ds_read_b128 v[186:189], v149 offset:18432
	ds_read_b128 v[206:209], v149 offset:19456
	ds_read_b128 v[210:213], v149 offset:20480
	ds_read_b128 v[214:217], v149 offset:21504
	ds_read_b128 v[218:221], v149 offset:22528
	ds_read_b128 v[222:225], v149 offset:23552
	global_load_lds_dwordx4 v192, s[62:63]
	s_add_i32 m0, s10, 0x2000
	s_add_u32 s10, s62, 0x40000
	s_addc_u32 s11, s63, 0
	s_add_i32 s12, s13, s7
	global_load_lds_dwordx4 v132, s[62:63]
	s_mov_b32 m0, s12
	s_nop 0
	global_load_lds_dwordx4 v192, s[10:11]
	s_add_i32 m0, s12, 0x2000
	s_nop 0
	global_load_lds_dwordx4 v132, s[10:11]
	s_waitcnt vmcnt(6)
	s_waitcnt lgkmcnt(0)
	s_barrier
	s_setprio 1
	s_waitcnt lgkmcnt(0)
	v_mfma_f32_16x16x32_bf16 v[60:63], v[138:141], v[178:181], 0
	v_mfma_f32_16x16x32_bf16 v[56:59], v[154:157], v[178:181], 0
	v_mfma_f32_16x16x32_bf16 v[44:47], v[138:141], v[186:189], 0
	v_mfma_f32_16x16x32_bf16 v[40:43], v[154:157], v[186:189], 0
	v_mfma_f32_16x16x32_bf16 v[28:31], v[138:141], v[210:213], 0
	v_mfma_f32_16x16x32_bf16 v[24:27], v[154:157], v[210:213], 0
	v_mfma_f32_16x16x32_bf16 v[12:15], v[138:141], v[218:221], 0
	v_mfma_f32_16x16x32_bf16 v[8:11], v[154:157], v[218:221], 0
	v_mfma_f32_16x16x32_bf16 v[60:63], v[150:153], v[182:185], v[60:63]
	v_mfma_f32_16x16x32_bf16 v[56:59], v[158:161], v[182:185], v[56:59]
	v_mfma_f32_16x16x32_bf16 v[44:47], v[150:153], v[206:209], v[44:47]
	v_mfma_f32_16x16x32_bf16 v[40:43], v[158:161], v[206:209], v[40:43]
	v_mfma_f32_16x16x32_bf16 v[28:31], v[150:153], v[214:217], v[28:31]
	v_mfma_f32_16x16x32_bf16 v[24:27], v[158:161], v[214:217], v[24:27]
	v_mfma_f32_16x16x32_bf16 v[12:15], v[150:153], v[222:225], v[12:15]
	v_mfma_f32_16x16x32_bf16 v[8:11], v[158:161], v[222:225], v[8:11]
	s_setprio 0
	s_setprio 1
	v_mfma_f32_16x16x32_bf16 v[52:55], v[162:165], v[178:181], 0
	v_mfma_f32_16x16x32_bf16 v[48:51], v[170:173], v[178:181], 0
	v_mfma_f32_16x16x32_bf16 v[36:39], v[162:165], v[186:189], 0
	v_mfma_f32_16x16x32_bf16 v[32:35], v[170:173], v[186:189], 0
	v_mfma_f32_16x16x32_bf16 v[20:23], v[162:165], v[210:213], 0
	v_mfma_f32_16x16x32_bf16 v[16:19], v[170:173], v[210:213], 0
	v_mfma_f32_16x16x32_bf16 v[4:7], v[162:165], v[218:221], 0
	v_mfma_f32_16x16x32_bf16 v[0:3], v[170:173], v[218:221], 0
	v_mfma_f32_16x16x32_bf16 v[52:55], v[166:169], v[182:185], v[52:55]
	v_mfma_f32_16x16x32_bf16 v[48:51], v[174:177], v[182:185], v[48:51]
	v_mfma_f32_16x16x32_bf16 v[36:39], v[166:169], v[206:209], v[36:39]
	v_mfma_f32_16x16x32_bf16 v[32:35], v[174:177], v[206:209], v[32:35]
	v_mfma_f32_16x16x32_bf16 v[20:23], v[166:169], v[214:217], v[20:23]
	v_mfma_f32_16x16x32_bf16 v[16:19], v[174:177], v[214:217], v[16:19]
	v_mfma_f32_16x16x32_bf16 v[4:7], v[166:169], v[222:225], v[4:7]
	v_mfma_f32_16x16x32_bf16 v[0:3], v[174:177], v[222:225], v[0:3]
	s_setprio 0
	s_barrier
	s_add_i32 s12, 0, 0x18000
	s_add_i32 s13, 0, 0x1c000
	v_add_u32_e32 v158, s12, v147
	v_add_u32_e32 v174, s13, v147
	ds_read_b128 v[138:141], v158
	ds_read_b128 v[150:153], v158 offset:1024
	ds_read_b128 v[154:157], v158 offset:2048
	ds_read_b128 v[158:161], v158 offset:3072
	ds_read_b128 v[162:165], v174
	ds_read_b128 v[166:169], v174 offset:1024
	ds_read_b128 v[170:173], v174 offset:2048
	ds_read_b128 v[174:177], v174 offset:3072
	s_mov_b32 m0, s8
	s_nop 0
	global_load_lds_dwordx4 v128, s[64:65]
	s_mov_b32 m0, s9
	s_nop 0
	global_load_lds_dwordx4 v130, s[64:65]
	s_add_u32 s10, s64, 0x40000
	s_addc_u32 s11, s65, 0
	s_mov_b32 m0, s26
	ds_read_b128 v[178:181], v149 offset:32768
	ds_read_b128 v[182:185], v149 offset:33792
	ds_read_b128 v[186:189], v149 offset:34816
	ds_read_b128 v[206:209], v149 offset:35840
	ds_read_b128 v[210:213], v149 offset:36864
	ds_read_b128 v[214:217], v149 offset:37888
	ds_read_b128 v[218:221], v149 offset:38912
	ds_read_b128 v[222:225], v149 offset:39936
	global_load_lds_dwordx4 v128, s[10:11]
	s_mov_b32 m0, s59
	s_nop 0
	global_load_lds_dwordx4 v130, s[10:11]
	s_waitcnt vmcnt(8)
	s_waitcnt lgkmcnt(0)
	s_barrier
	s_setprio 1
	s_waitcnt lgkmcnt(0)
	v_mfma_f32_16x16x32_bf16 v[124:127], v[138:141], v[178:181], v[124:127]
	v_mfma_f32_16x16x32_bf16 v[120:123], v[154:157], v[178:181], v[120:123]
	v_mfma_f32_16x16x32_bf16 v[108:111], v[138:141], v[186:189], v[108:111]
	v_mfma_f32_16x16x32_bf16 v[104:107], v[154:157], v[186:189], v[104:107]
	v_mfma_f32_16x16x32_bf16 v[92:95], v[138:141], v[210:213], v[92:95]
	v_mfma_f32_16x16x32_bf16 v[88:91], v[154:157], v[210:213], v[88:91]
	v_mfma_f32_16x16x32_bf16 v[76:79], v[138:141], v[218:221], v[76:79]
	v_mfma_f32_16x16x32_bf16 v[72:75], v[154:157], v[218:221], v[72:75]
	v_mfma_f32_16x16x32_bf16 v[124:127], v[150:153], v[182:185], v[124:127]
	v_mfma_f32_16x16x32_bf16 v[120:123], v[158:161], v[182:185], v[120:123]
	v_mfma_f32_16x16x32_bf16 v[108:111], v[150:153], v[206:209], v[108:111]
	v_mfma_f32_16x16x32_bf16 v[104:107], v[158:161], v[206:209], v[104:107]
	v_mfma_f32_16x16x32_bf16 v[92:95], v[150:153], v[214:217], v[92:95]
	v_mfma_f32_16x16x32_bf16 v[88:91], v[158:161], v[214:217], v[88:91]
	v_mfma_f32_16x16x32_bf16 v[76:79], v[150:153], v[222:225], v[76:79]
	v_mfma_f32_16x16x32_bf16 v[72:75], v[158:161], v[222:225], v[72:75]
	s_setprio 0
	s_setprio 1
	v_mfma_f32_16x16x32_bf16 v[116:119], v[162:165], v[178:181], v[116:119]
	v_mfma_f32_16x16x32_bf16 v[112:115], v[170:173], v[178:181], v[112:115]
	v_mfma_f32_16x16x32_bf16 v[100:103], v[162:165], v[186:189], v[100:103]
	v_mfma_f32_16x16x32_bf16 v[96:99], v[170:173], v[186:189], v[96:99]
	v_mfma_f32_16x16x32_bf16 v[84:87], v[162:165], v[210:213], v[84:87]
	v_mfma_f32_16x16x32_bf16 v[80:83], v[170:173], v[210:213], v[80:83]
	v_mfma_f32_16x16x32_bf16 v[68:71], v[162:165], v[218:221], v[68:71]
	v_mfma_f32_16x16x32_bf16 v[64:67], v[170:173], v[218:221], v[64:67]
	v_mfma_f32_16x16x32_bf16 v[116:119], v[166:169], v[182:185], v[116:119]
	v_mfma_f32_16x16x32_bf16 v[112:115], v[174:177], v[182:185], v[112:115]
	v_mfma_f32_16x16x32_bf16 v[100:103], v[166:169], v[206:209], v[100:103]
	v_mfma_f32_16x16x32_bf16 v[96:99], v[174:177], v[206:209], v[96:99]
	v_mfma_f32_16x16x32_bf16 v[84:87], v[166:169], v[214:217], v[84:87]
	v_mfma_f32_16x16x32_bf16 v[80:83], v[174:177], v[214:217], v[80:83]
	v_mfma_f32_16x16x32_bf16 v[68:71], v[166:169], v[222:225], v[68:71]
	v_mfma_f32_16x16x32_bf16 v[64:67], v[174:177], v[222:225], v[64:67]
	s_setprio 0
	s_barrier
	s_add_i32 s10, s12, s7
	s_add_i32 m0, s10, 0xffffff80
	ds_read_b128 v[178:181], v149 offset:49152
	ds_read_b128 v[182:185], v149 offset:50176
	ds_read_b128 v[186:189], v149 offset:51200
	ds_read_b128 v[206:209], v149 offset:52224
	ds_read_b128 v[210:213], v149 offset:53248
	ds_read_b128 v[214:217], v149 offset:54272
	ds_read_b128 v[218:221], v149 offset:55296
	ds_read_b128 v[222:225], v149 offset:56320
	global_load_lds_dwordx4 v192, s[62:63] offset:128
	s_add_i32 m0, s10, 0x1f80
	s_add_u32 s10, s62, 0x40080
	s_addc_u32 s11, s63, 0
	s_add_i32 s12, s13, s7
	global_load_lds_dwordx4 v132, s[62:63] offset:128
	s_mov_b32 m0, s12
	s_nop 0
	global_load_lds_dwordx4 v192, s[10:11]
	s_add_i32 m0, s12, 0x2000
	s_nop 0
	global_load_lds_dwordx4 v132, s[10:11]
	s_waitcnt vmcnt(6)
	s_waitcnt lgkmcnt(0)
	s_barrier
	s_setprio 1
	s_waitcnt lgkmcnt(0)
	v_mfma_f32_16x16x32_bf16 v[60:63], v[138:141], v[178:181], v[60:63]
	v_mfma_f32_16x16x32_bf16 v[56:59], v[154:157], v[178:181], v[56:59]
	v_mfma_f32_16x16x32_bf16 v[44:47], v[138:141], v[186:189], v[44:47]
	v_mfma_f32_16x16x32_bf16 v[40:43], v[154:157], v[186:189], v[40:43]
	v_mfma_f32_16x16x32_bf16 v[28:31], v[138:141], v[210:213], v[28:31]
	v_mfma_f32_16x16x32_bf16 v[24:27], v[154:157], v[210:213], v[24:27]
	v_mfma_f32_16x16x32_bf16 v[12:15], v[138:141], v[218:221], v[12:15]
	v_mfma_f32_16x16x32_bf16 v[8:11], v[154:157], v[218:221], v[8:11]
	v_mfma_f32_16x16x32_bf16 v[60:63], v[150:153], v[182:185], v[60:63]
	v_mfma_f32_16x16x32_bf16 v[56:59], v[158:161], v[182:185], v[56:59]
	v_mfma_f32_16x16x32_bf16 v[44:47], v[150:153], v[206:209], v[44:47]
	v_mfma_f32_16x16x32_bf16 v[40:43], v[158:161], v[206:209], v[40:43]
	v_mfma_f32_16x16x32_bf16 v[28:31], v[150:153], v[214:217], v[28:31]
	v_mfma_f32_16x16x32_bf16 v[24:27], v[158:161], v[214:217], v[24:27]
	v_mfma_f32_16x16x32_bf16 v[12:15], v[150:153], v[222:225], v[12:15]
	v_mfma_f32_16x16x32_bf16 v[8:11], v[158:161], v[222:225], v[8:11]
	s_setprio 0
	s_setprio 1
	v_mfma_f32_16x16x32_bf16 v[52:55], v[162:165], v[178:181], v[52:55]
	v_mfma_f32_16x16x32_bf16 v[48:51], v[170:173], v[178:181], v[48:51]
	v_mfma_f32_16x16x32_bf16 v[36:39], v[162:165], v[186:189], v[36:39]
	v_mfma_f32_16x16x32_bf16 v[32:35], v[170:173], v[186:189], v[32:35]
	v_mfma_f32_16x16x32_bf16 v[20:23], v[162:165], v[210:213], v[20:23]
	v_mfma_f32_16x16x32_bf16 v[16:19], v[170:173], v[210:213], v[16:19]
	v_mfma_f32_16x16x32_bf16 v[4:7], v[162:165], v[218:221], v[4:7]
	v_mfma_f32_16x16x32_bf16 v[0:3], v[170:173], v[218:221], v[0:3]
	v_mfma_f32_16x16x32_bf16 v[52:55], v[166:169], v[182:185], v[52:55]
	v_mfma_f32_16x16x32_bf16 v[48:51], v[174:177], v[182:185], v[48:51]
	v_mfma_f32_16x16x32_bf16 v[36:39], v[166:169], v[206:209], v[36:39]
	v_mfma_f32_16x16x32_bf16 v[32:35], v[174:177], v[206:209], v[32:35]
	v_mfma_f32_16x16x32_bf16 v[20:23], v[166:169], v[214:217], v[20:23]
	v_mfma_f32_16x16x32_bf16 v[16:19], v[174:177], v[214:217], v[16:19]
	v_mfma_f32_16x16x32_bf16 v[4:7], v[166:169], v[222:225], v[4:7]
	v_mfma_f32_16x16x32_bf16 v[0:3], v[174:177], v[222:225], v[0:3]
	s_setprio 0
	s_barrier
	s_add_i32 s96, s96, 2
	s_add_u32 s60, s60, 0x100
	s_addc_u32 s61, s61, 0
	s_add_u32 s83, s83, 0x100
	s_addc_u32 s95, s95, 0
	s_cmp_gt_u32 s96, 13

.LBB0_1143:
	s_ashr_i32 s49, s48, 31
	s_lshl_b64 s[6:7], s[48:49], 19
	s_add_u32 s50, s60, s6
	s_addc_u32 s51, s61, s7
	s_and_b64 s[6:7], s[38:39], exec
	s_cselect_b32 s5, s51, s31
	s_cselect_b32 s6, s50, s30
	s_ashr_i32 s47, s46, 31
	s_lshl_b64 s[8:9], s[46:47], 19
	s_add_u32 s52, s57, s8
	s_addc_u32 s53, s58, s9
	s_and_b64 s[8:9], s[38:39], exec
	s_cselect_b32 s7, s53, s41
	s_cselect_b32 s8, s52, s40
	s_add_u32 s30, s30, 0x40080
	s_addc_u32 s31, s31, 0
	s_add_u32 s9, s40, 0x100
	s_addc_u32 s23, s41, 0
	s_mov_b32 s47, -2
	s_add_u32 s10, s30, 0xfffc0080
	s_addc_u32 s11, s31, -1
	s_add_i32 s12, 0, 0x10000
	s_cmp_eq_u32 s47, 12
	s_cselect_b32 s55, s5, s11
	s_cselect_b32 s54, s6, s10
	v_add_u32_e32 v146, s12, v150
	s_cselect_b32 s41, s7, s23
	s_cselect_b32 s40, s8, s9
	s_add_i32 s13, 0, 0x14000
	ds_read_b128 v[138:141], v146
	ds_read_b128 v[142:145], v146 offset:1024
	ds_read_b128 v[154:157], v146 offset:2048
	ds_read_b128 v[158:161], v146 offset:3072
	v_add_u32_e32 v146, s13, v150
	ds_read_b128 v[162:165], v146
	ds_read_b128 v[166:169], v146 offset:1024
	ds_read_b128 v[170:173], v146 offset:2048
	ds_read_b128 v[174:177], v146 offset:3072
	s_add_u32 s10, s30, 0xfffc0000
	s_addc_u32 s11, s31, -1
	s_mov_b32 m0, s26
	s_nop 0
	global_load_lds_dwordx4 v134, s[10:11]
	s_mov_b32 m0, s67
	s_nop 0
	global_load_lds_dwordx4 v136, s[10:11]
	s_add_i32 m0, s63, 0xc000
	ds_read_b128 v[178:181], v152
	ds_read_b128 v[182:185], v152 offset:1024
	ds_read_b128 v[186:189], v152 offset:2048
	ds_read_b128 v[206:209], v152 offset:3072
	ds_read_b128 v[210:213], v152 offset:4096
	ds_read_b128 v[214:217], v152 offset:5120
	ds_read_b128 v[218:221], v152 offset:6144
	ds_read_b128 v[222:225], v152 offset:7168
	global_load_lds_dwordx4 v134, s[30:31]
	s_add_i32 m0, s63, 0xe000
	s_nop 0
	global_load_lds_dwordx4 v136, s[30:31]
	s_waitcnt vmcnt(8)
	s_waitcnt lgkmcnt(0)
	s_barrier
	s_setprio 1
	s_waitcnt lgkmcnt(0)
	v_mfma_f32_16x16x32_bf16 v[124:127], v[138:141], v[178:181], 0
	v_mfma_f32_16x16x32_bf16 v[120:123], v[154:157], v[178:181], 0
	v_mfma_f32_16x16x32_bf16 v[108:111], v[138:141], v[186:189], 0
	v_mfma_f32_16x16x32_bf16 v[104:107], v[154:157], v[186:189], 0
	v_mfma_f32_16x16x32_bf16 v[92:95], v[138:141], v[210:213], 0
	v_mfma_f32_16x16x32_bf16 v[88:91], v[154:157], v[210:213], 0
	v_mfma_f32_16x16x32_bf16 v[76:79], v[138:141], v[218:221], 0
	v_mfma_f32_16x16x32_bf16 v[72:75], v[154:157], v[218:221], 0
	v_mfma_f32_16x16x32_bf16 v[124:127], v[142:145], v[182:185], v[124:127]
	v_mfma_f32_16x16x32_bf16 v[120:123], v[158:161], v[182:185], v[120:123]
	v_mfma_f32_16x16x32_bf16 v[108:111], v[142:145], v[206:209], v[108:111]
	v_mfma_f32_16x16x32_bf16 v[104:107], v[158:161], v[206:209], v[104:107]
	v_mfma_f32_16x16x32_bf16 v[92:95], v[142:145], v[214:217], v[92:95]
	v_mfma_f32_16x16x32_bf16 v[88:91], v[158:161], v[214:217], v[88:91]
	v_mfma_f32_16x16x32_bf16 v[76:79], v[142:145], v[222:225], v[76:79]
	v_mfma_f32_16x16x32_bf16 v[72:75], v[158:161], v[222:225], v[72:75]
	s_setprio 0
	s_setprio 1
	v_mfma_f32_16x16x32_bf16 v[116:119], v[162:165], v[178:181], 0
	v_mfma_f32_16x16x32_bf16 v[112:115], v[170:173], v[178:181], 0
	v_mfma_f32_16x16x32_bf16 v[100:103], v[162:165], v[186:189], 0
	v_mfma_f32_16x16x32_bf16 v[96:99], v[170:173], v[186:189], 0
	v_mfma_f32_16x16x32_bf16 v[84:87], v[162:165], v[210:213], 0
	v_mfma_f32_16x16x32_bf16 v[80:83], v[170:173], v[210:213], 0
	v_mfma_f32_16x16x32_bf16 v[68:71], v[162:165], v[218:221], 0
	v_mfma_f32_16x16x32_bf16 v[64:67], v[170:173], v[218:221], 0
	v_mfma_f32_16x16x32_bf16 v[116:119], v[166:169], v[182:185], v[116:119]
	v_mfma_f32_16x16x32_bf16 v[112:115], v[174:177], v[182:185], v[112:115]
	v_mfma_f32_16x16x32_bf16 v[100:103], v[166:169], v[206:209], v[100:103]
	v_mfma_f32_16x16x32_bf16 v[96:99], v[174:177], v[206:209], v[96:99]
	v_mfma_f32_16x16x32_bf16 v[84:87], v[166:169], v[214:217], v[84:87]
	v_mfma_f32_16x16x32_bf16 v[80:83], v[174:177], v[214:217], v[80:83]
	v_mfma_f32_16x16x32_bf16 v[68:71], v[166:169], v[222:225], v[68:71]
	v_mfma_f32_16x16x32_bf16 v[64:67], v[174:177], v[222:225], v[64:67]
	s_setprio 0
	s_barrier
	s_add_i32 s10, s12, s62
	s_mov_b32 m0, s10
	ds_read_b128 v[178:181], v152 offset:16384
	ds_read_b128 v[182:185], v152 offset:17408
	ds_read_b128 v[186:189], v152 offset:18432
	ds_read_b128 v[206:209], v152 offset:19456
	ds_read_b128 v[210:213], v152 offset:20480
	ds_read_b128 v[214:217], v152 offset:21504
	ds_read_b128 v[218:221], v152 offset:22528
	ds_read_b128 v[222:225], v152 offset:23552
	global_load_lds_dwordx4 v192, s[40:41]
	s_add_i32 m0, s10, 0x2000
	s_add_u32 s10, s40, 0x40000
	s_addc_u32 s11, s41, 0
	s_add_i32 s12, s13, s62
	global_load_lds_dwordx4 v132, s[40:41]
	s_mov_b32 m0, s12
	s_nop 0
	global_load_lds_dwordx4 v192, s[10:11]
	s_add_i32 m0, s12, 0x2000
	s_nop 0
	global_load_lds_dwordx4 v132, s[10:11]
	s_waitcnt vmcnt(6)
	s_waitcnt lgkmcnt(0)
	s_barrier
	s_setprio 1
	s_waitcnt lgkmcnt(0)
	v_mfma_f32_16x16x32_bf16 v[60:63], v[138:141], v[178:181], 0
	v_mfma_f32_16x16x32_bf16 v[56:59], v[154:157], v[178:181], 0
	v_mfma_f32_16x16x32_bf16 v[44:47], v[138:141], v[186:189], 0
	v_mfma_f32_16x16x32_bf16 v[40:43], v[154:157], v[186:189], 0
	v_mfma_f32_16x16x32_bf16 v[28:31], v[138:141], v[210:213], 0
	v_mfma_f32_16x16x32_bf16 v[24:27], v[154:157], v[210:213], 0
	v_mfma_f32_16x16x32_bf16 v[12:15], v[138:141], v[218:221], 0
	v_mfma_f32_16x16x32_bf16 v[8:11], v[154:157], v[218:221], 0
	v_mfma_f32_16x16x32_bf16 v[60:63], v[142:145], v[182:185], v[60:63]
	v_mfma_f32_16x16x32_bf16 v[56:59], v[158:161], v[182:185], v[56:59]
	v_mfma_f32_16x16x32_bf16 v[44:47], v[142:145], v[206:209], v[44:47]
	v_mfma_f32_16x16x32_bf16 v[40:43], v[158:161], v[206:209], v[40:43]
	v_mfma_f32_16x16x32_bf16 v[28:31], v[142:145], v[214:217], v[28:31]
	v_mfma_f32_16x16x32_bf16 v[24:27], v[158:161], v[214:217], v[24:27]
	v_mfma_f32_16x16x32_bf16 v[12:15], v[142:145], v[222:225], v[12:15]
	v_mfma_f32_16x16x32_bf16 v[8:11], v[158:161], v[222:225], v[8:11]
	s_setprio 0
	s_setprio 1
	v_mfma_f32_16x16x32_bf16 v[52:55], v[162:165], v[178:181], 0
	v_mfma_f32_16x16x32_bf16 v[48:51], v[170:173], v[178:181], 0
	v_mfma_f32_16x16x32_bf16 v[36:39], v[162:165], v[186:189], 0
	v_mfma_f32_16x16x32_bf16 v[32:35], v[170:173], v[186:189], 0
	v_mfma_f32_16x16x32_bf16 v[20:23], v[162:165], v[210:213], 0
	v_mfma_f32_16x16x32_bf16 v[16:19], v[170:173], v[210:213], 0
	v_mfma_f32_16x16x32_bf16 v[4:7], v[162:165], v[218:221], 0
	v_mfma_f32_16x16x32_bf16 v[0:3], v[170:173], v[218:221], 0
	v_mfma_f32_16x16x32_bf16 v[52:55], v[166:169], v[182:185], v[52:55]
	v_mfma_f32_16x16x32_bf16 v[48:51], v[174:177], v[182:185], v[48:51]
	v_mfma_f32_16x16x32_bf16 v[36:39], v[166:169], v[206:209], v[36:39]
	v_mfma_f32_16x16x32_bf16 v[32:35], v[174:177], v[206:209], v[32:35]
	v_mfma_f32_16x16x32_bf16 v[20:23], v[166:169], v[214:217], v[20:23]
	v_mfma_f32_16x16x32_bf16 v[16:19], v[174:177], v[214:217], v[16:19]
	v_mfma_f32_16x16x32_bf16 v[4:7], v[166:169], v[222:225], v[4:7]
	v_mfma_f32_16x16x32_bf16 v[0:3], v[174:177], v[222:225], v[0:3]
	s_setprio 0
	s_barrier
	s_add_i32 s12, 0, 0x18000
	v_add_u32_e32 v146, s12, v150
	s_add_i32 s13, 0, 0x1c000
	ds_read_b128 v[138:141], v146
	ds_read_b128 v[142:145], v146 offset:1024
	ds_read_b128 v[154:157], v146 offset:2048
	ds_read_b128 v[158:161], v146 offset:3072
	v_add_u32_e32 v146, s13, v150
	ds_read_b128 v[162:165], v146
	ds_read_b128 v[166:169], v146 offset:1024
	ds_read_b128 v[170:173], v146 offset:2048
	ds_read_b128 v[174:177], v146 offset:3072
	s_mov_b32 m0, s63
	s_nop 0
	global_load_lds_dwordx4 v128, s[54:55]
	s_mov_b32 m0, s64
	s_nop 0
	global_load_lds_dwordx4 v130, s[54:55]
	s_add_u32 s10, s54, 0x40000
	s_addc_u32 s11, s55, 0
	s_mov_b32 m0, s65
	ds_read_b128 v[178:181], v152 offset:32768
	ds_read_b128 v[182:185], v152 offset:33792
	ds_read_b128 v[186:189], v152 offset:34816
	ds_read_b128 v[206:209], v152 offset:35840
	ds_read_b128 v[210:213], v152 offset:36864
	ds_read_b128 v[214:217], v152 offset:37888
	ds_read_b128 v[218:221], v152 offset:38912
	ds_read_b128 v[222:225], v152 offset:39936
	global_load_lds_dwordx4 v128, s[10:11]
	s_mov_b32 m0, s66
	s_nop 0
	global_load_lds_dwordx4 v130, s[10:11]
	s_waitcnt vmcnt(8)
	s_waitcnt lgkmcnt(0)
	s_barrier
	s_setprio 1
	s_waitcnt lgkmcnt(0)
	v_mfma_f32_16x16x32_bf16 v[124:127], v[138:141], v[178:181], v[124:127]
	v_mfma_f32_16x16x32_bf16 v[120:123], v[154:157], v[178:181], v[120:123]
	v_mfma_f32_16x16x32_bf16 v[108:111], v[138:141], v[186:189], v[108:111]
	v_mfma_f32_16x16x32_bf16 v[104:107], v[154:157], v[186:189], v[104:107]
	v_mfma_f32_16x16x32_bf16 v[92:95], v[138:141], v[210:213], v[92:95]
	v_mfma_f32_16x16x32_bf16 v[88:91], v[154:157], v[210:213], v[88:91]
	v_mfma_f32_16x16x32_bf16 v[76:79], v[138:141], v[218:221], v[76:79]
	v_mfma_f32_16x16x32_bf16 v[72:75], v[154:157], v[218:221], v[72:75]
	v_mfma_f32_16x16x32_bf16 v[124:127], v[142:145], v[182:185], v[124:127]
	v_mfma_f32_16x16x32_bf16 v[120:123], v[158:161], v[182:185], v[120:123]
	v_mfma_f32_16x16x32_bf16 v[108:111], v[142:145], v[206:209], v[108:111]
	v_mfma_f32_16x16x32_bf16 v[104:107], v[158:161], v[206:209], v[104:107]
	v_mfma_f32_16x16x32_bf16 v[92:95], v[142:145], v[214:217], v[92:95]
	v_mfma_f32_16x16x32_bf16 v[88:91], v[158:161], v[214:217], v[88:91]
	v_mfma_f32_16x16x32_bf16 v[76:79], v[142:145], v[222:225], v[76:79]
	v_mfma_f32_16x16x32_bf16 v[72:75], v[158:161], v[222:225], v[72:75]
	s_setprio 0
	s_setprio 1
	v_mfma_f32_16x16x32_bf16 v[116:119], v[162:165], v[178:181], v[116:119]
	v_mfma_f32_16x16x32_bf16 v[112:115], v[170:173], v[178:181], v[112:115]
	v_mfma_f32_16x16x32_bf16 v[100:103], v[162:165], v[186:189], v[100:103]
	v_mfma_f32_16x16x32_bf16 v[96:99], v[170:173], v[186:189], v[96:99]
	v_mfma_f32_16x16x32_bf16 v[84:87], v[162:165], v[210:213], v[84:87]
	v_mfma_f32_16x16x32_bf16 v[80:83], v[170:173], v[210:213], v[80:83]
	v_mfma_f32_16x16x32_bf16 v[68:71], v[162:165], v[218:221], v[68:71]
	v_mfma_f32_16x16x32_bf16 v[64:67], v[170:173], v[218:221], v[64:67]
	v_mfma_f32_16x16x32_bf16 v[116:119], v[166:169], v[182:185], v[116:119]
	v_mfma_f32_16x16x32_bf16 v[112:115], v[174:177], v[182:185], v[112:115]
	v_mfma_f32_16x16x32_bf16 v[100:103], v[166:169], v[206:209], v[100:103]
	v_mfma_f32_16x16x32_bf16 v[96:99], v[174:177], v[206:209], v[96:99]
	v_mfma_f32_16x16x32_bf16 v[84:87], v[166:169], v[214:217], v[84:87]
	v_mfma_f32_16x16x32_bf16 v[80:83], v[174:177], v[214:217], v[80:83]
	v_mfma_f32_16x16x32_bf16 v[68:71], v[166:169], v[222:225], v[68:71]
	v_mfma_f32_16x16x32_bf16 v[64:67], v[174:177], v[222:225], v[64:67]
	s_setprio 0
	s_barrier
	s_add_i32 s10, s12, s62
	s_add_i32 m0, s10, 0xffffff80
	ds_read_b128 v[178:181], v152 offset:49152
	ds_read_b128 v[182:185], v152 offset:50176
	ds_read_b128 v[186:189], v152 offset:51200
	ds_read_b128 v[206:209], v152 offset:52224
	ds_read_b128 v[210:213], v152 offset:53248
	ds_read_b128 v[214:217], v152 offset:54272
	ds_read_b128 v[218:221], v152 offset:55296
	ds_read_b128 v[222:225], v152 offset:56320
	global_load_lds_dwordx4 v192, s[40:41] offset:128
	s_add_i32 m0, s10, 0x1f80
	s_add_u32 s10, s40, 0x40080
	s_addc_u32 s11, s41, 0
	s_add_i32 s12, s13, s62
	global_load_lds_dwordx4 v132, s[40:41] offset:128
	s_mov_b32 m0, s12
	s_nop 0
	global_load_lds_dwordx4 v192, s[10:11]
	s_add_i32 m0, s12, 0x2000
	s_nop 0
	global_load_lds_dwordx4 v132, s[10:11]
	s_waitcnt vmcnt(6)
	s_waitcnt lgkmcnt(0)
	s_barrier
	s_setprio 1
	s_waitcnt lgkmcnt(0)
	v_mfma_f32_16x16x32_bf16 v[60:63], v[138:141], v[178:181], v[60:63]
	v_mfma_f32_16x16x32_bf16 v[56:59], v[154:157], v[178:181], v[56:59]
	v_mfma_f32_16x16x32_bf16 v[44:47], v[138:141], v[186:189], v[44:47]
	v_mfma_f32_16x16x32_bf16 v[40:43], v[154:157], v[186:189], v[40:43]
	v_mfma_f32_16x16x32_bf16 v[28:31], v[138:141], v[210:213], v[28:31]
	v_mfma_f32_16x16x32_bf16 v[24:27], v[154:157], v[210:213], v[24:27]
	v_mfma_f32_16x16x32_bf16 v[12:15], v[138:141], v[218:221], v[12:15]
	v_mfma_f32_16x16x32_bf16 v[8:11], v[154:157], v[218:221], v[8:11]
	v_mfma_f32_16x16x32_bf16 v[60:63], v[142:145], v[182:185], v[60:63]
	v_mfma_f32_16x16x32_bf16 v[56:59], v[158:161], v[182:185], v[56:59]
	v_mfma_f32_16x16x32_bf16 v[44:47], v[142:145], v[206:209], v[44:47]
	v_mfma_f32_16x16x32_bf16 v[40:43], v[158:161], v[206:209], v[40:43]
	v_mfma_f32_16x16x32_bf16 v[28:31], v[142:145], v[214:217], v[28:31]
	v_mfma_f32_16x16x32_bf16 v[24:27], v[158:161], v[214:217], v[24:27]
	v_mfma_f32_16x16x32_bf16 v[12:15], v[142:145], v[222:225], v[12:15]
	v_mfma_f32_16x16x32_bf16 v[8:11], v[158:161], v[222:225], v[8:11]
	s_setprio 0
	s_setprio 1
	v_mfma_f32_16x16x32_bf16 v[52:55], v[162:165], v[178:181], v[52:55]
	v_mfma_f32_16x16x32_bf16 v[48:51], v[170:173], v[178:181], v[48:51]
	v_mfma_f32_16x16x32_bf16 v[36:39], v[162:165], v[186:189], v[36:39]
	v_mfma_f32_16x16x32_bf16 v[32:35], v[170:173], v[186:189], v[32:35]
	v_mfma_f32_16x16x32_bf16 v[20:23], v[162:165], v[210:213], v[20:23]
	v_mfma_f32_16x16x32_bf16 v[16:19], v[170:173], v[210:213], v[16:19]
	v_mfma_f32_16x16x32_bf16 v[4:7], v[162:165], v[218:221], v[4:7]
	v_mfma_f32_16x16x32_bf16 v[0:3], v[170:173], v[218:221], v[0:3]
	v_mfma_f32_16x16x32_bf16 v[52:55], v[166:169], v[182:185], v[52:55]
	v_mfma_f32_16x16x32_bf16 v[48:51], v[174:177], v[182:185], v[48:51]
	v_mfma_f32_16x16x32_bf16 v[36:39], v[166:169], v[206:209], v[36:39]
	v_mfma_f32_16x16x32_bf16 v[32:35], v[174:177], v[206:209], v[32:35]
	v_mfma_f32_16x16x32_bf16 v[20:23], v[166:169], v[214:217], v[20:23]
	v_mfma_f32_16x16x32_bf16 v[16:19], v[174:177], v[214:217], v[16:19]
	v_mfma_f32_16x16x32_bf16 v[4:7], v[166:169], v[222:225], v[4:7]
	v_mfma_f32_16x16x32_bf16 v[0:3], v[174:177], v[222:225], v[0:3]
	s_setprio 0
	s_barrier
	s_add_i32 s47, s47, 2
	s_add_u32 s30, s30, 0x100
	s_addc_u32 s31, s31, 0
	s_add_u32 s9, s9, 0x100
	s_addc_u32 s23, s23, 0
	s_cmp_gt_u32 s47, 13

.LBB0_1228:
	s_ashr_i32 s47, s46, 31
	s_lshl_b64 s[10:11], s[46:47], 21
	s_add_u32 s48, s34, s10
	s_addc_u32 s49, s35, s11
	s_and_b64 s[10:11], s[40:41], exec
	s_cselect_b32 s47, s49, s57
	s_cselect_b32 s53, s48, s56
	s_ashr_i32 s45, s44, 31
	s_lshl_b64 s[10:11], s[44:45], 21
	s_add_u32 s50, s4, s10
	s_addc_u32 s51, s5, s11
	s_and_b64 s[10:11], s[40:41], exec
	s_cselect_b32 s45, s51, s59
	s_cselect_b32 s78, s50, s58
	s_add_u32 s56, s56, 0x100080
	s_addc_u32 s57, s57, 0
	s_add_u32 s79, s58, 0x100
	s_addc_u32 s82, s59, 0
	s_mov_b32 s83, -2
	s_waitcnt lgkmcnt(0)
	s_add_u32 s10, s56, 0xfff00080
	s_addc_u32 s11, s57, -1
	s_add_i32 s12, 0, 0x10000
	s_cmp_eq_u32 s83, 60
	s_cselect_b32 s61, s47, s11
	s_cselect_b32 s60, s53, s10
	s_cselect_b32 s59, s45, s82
	s_cselect_b32 s58, s78, s79
	s_add_i32 s13, 0, 0x14000
	v_add_u32_e32 v156, s12, v145
	v_add_u32_e32 v172, s13, v145
	ds_read_b128 v[138:141], v156
	ds_read_b128 v[148:151], v156 offset:1024
	ds_read_b128 v[152:155], v156 offset:2048
	ds_read_b128 v[156:159], v156 offset:3072
	ds_read_b128 v[160:163], v172
	ds_read_b128 v[164:167], v172 offset:1024
	ds_read_b128 v[168:171], v172 offset:2048
	ds_read_b128 v[172:175], v172 offset:3072
	s_add_u32 s10, s56, 0xfff00000
	s_addc_u32 s11, s57, -1
	s_mov_b32 m0, s64
	s_nop 0
	global_load_lds_dwordx4 v134, s[10:11]
	s_mov_b32 m0, s65
	s_nop 0
	global_load_lds_dwordx4 v136, s[10:11]
	s_add_i32 m0, s9, 0xc000
	ds_read_b128 v[176:179], v147
	ds_read_b128 v[180:183], v147 offset:1024
	ds_read_b128 v[184:187], v147 offset:2048
	ds_read_b128 v[188:191], v147 offset:3072
	ds_read_b128 v[206:209], v147 offset:4096
	ds_read_b128 v[210:213], v147 offset:5120
	ds_read_b128 v[214:217], v147 offset:6144
	ds_read_b128 v[218:221], v147 offset:7168
	global_load_lds_dwordx4 v134, s[56:57]
	s_add_i32 m0, s9, 0xe000
	s_nop 0
	global_load_lds_dwordx4 v136, s[56:57]
	s_waitcnt vmcnt(8)
	s_waitcnt lgkmcnt(0)
	s_barrier
	s_setprio 1
	s_waitcnt lgkmcnt(0)
	v_mfma_f32_16x16x32_bf16 v[124:127], v[138:141], v[176:179], 0
	v_mfma_f32_16x16x32_bf16 v[120:123], v[152:155], v[176:179], 0
	v_mfma_f32_16x16x32_bf16 v[108:111], v[138:141], v[184:187], 0
	v_mfma_f32_16x16x32_bf16 v[104:107], v[152:155], v[184:187], 0
	v_mfma_f32_16x16x32_bf16 v[92:95], v[138:141], v[206:209], 0
	v_mfma_f32_16x16x32_bf16 v[88:91], v[152:155], v[206:209], 0
	v_mfma_f32_16x16x32_bf16 v[76:79], v[138:141], v[214:217], 0
	v_mfma_f32_16x16x32_bf16 v[72:75], v[152:155], v[214:217], 0
	v_mfma_f32_16x16x32_bf16 v[124:127], v[148:151], v[180:183], v[124:127]
	v_mfma_f32_16x16x32_bf16 v[120:123], v[156:159], v[180:183], v[120:123]
	v_mfma_f32_16x16x32_bf16 v[108:111], v[148:151], v[188:191], v[108:111]
	v_mfma_f32_16x16x32_bf16 v[104:107], v[156:159], v[188:191], v[104:107]
	v_mfma_f32_16x16x32_bf16 v[92:95], v[148:151], v[210:213], v[92:95]
	v_mfma_f32_16x16x32_bf16 v[88:91], v[156:159], v[210:213], v[88:91]
	v_mfma_f32_16x16x32_bf16 v[76:79], v[148:151], v[218:221], v[76:79]
	v_mfma_f32_16x16x32_bf16 v[72:75], v[156:159], v[218:221], v[72:75]
	s_setprio 0
	s_setprio 1
	v_mfma_f32_16x16x32_bf16 v[116:119], v[160:163], v[176:179], 0
	v_mfma_f32_16x16x32_bf16 v[112:115], v[168:171], v[176:179], 0
	v_mfma_f32_16x16x32_bf16 v[100:103], v[160:163], v[184:187], 0
	v_mfma_f32_16x16x32_bf16 v[96:99], v[168:171], v[184:187], 0
	v_mfma_f32_16x16x32_bf16 v[84:87], v[160:163], v[206:209], 0
	v_mfma_f32_16x16x32_bf16 v[80:83], v[168:171], v[206:209], 0
	v_mfma_f32_16x16x32_bf16 v[68:71], v[160:163], v[214:217], 0
	v_mfma_f32_16x16x32_bf16 v[64:67], v[168:171], v[214:217], 0
	v_mfma_f32_16x16x32_bf16 v[116:119], v[164:167], v[180:183], v[116:119]
	v_mfma_f32_16x16x32_bf16 v[112:115], v[172:175], v[180:183], v[112:115]
	v_mfma_f32_16x16x32_bf16 v[100:103], v[164:167], v[188:191], v[100:103]
	v_mfma_f32_16x16x32_bf16 v[96:99], v[172:175], v[188:191], v[96:99]
	v_mfma_f32_16x16x32_bf16 v[84:87], v[164:167], v[210:213], v[84:87]
	v_mfma_f32_16x16x32_bf16 v[80:83], v[172:175], v[210:213], v[80:83]
	v_mfma_f32_16x16x32_bf16 v[68:71], v[164:167], v[218:221], v[68:71]
	v_mfma_f32_16x16x32_bf16 v[64:67], v[172:175], v[218:221], v[64:67]
	s_setprio 0
	s_barrier
	s_add_i32 s10, s12, s8
	s_mov_b32 m0, s10
	ds_read_b128 v[176:179], v147 offset:16384
	ds_read_b128 v[180:183], v147 offset:17408
	ds_read_b128 v[184:187], v147 offset:18432
	ds_read_b128 v[188:191], v147 offset:19456
	ds_read_b128 v[206:209], v147 offset:20480
	ds_read_b128 v[210:213], v147 offset:21504
	ds_read_b128 v[214:217], v147 offset:22528
	ds_read_b128 v[218:221], v147 offset:23552
	global_load_lds_dwordx4 v192, s[58:59]
	s_add_i32 m0, s10, 0x2000
	s_add_u32 s10, s58, 0x100000
	s_addc_u32 s11, s59, 0
	s_add_i32 s12, s13, s8
	global_load_lds_dwordx4 v132, s[58:59]
	s_mov_b32 m0, s12
	s_nop 0
	global_load_lds_dwordx4 v192, s[10:11]
	s_add_i32 m0, s12, 0x2000
	s_nop 0
	global_load_lds_dwordx4 v132, s[10:11]
	s_waitcnt vmcnt(6)
	s_waitcnt lgkmcnt(0)
	s_barrier
	s_setprio 1
	s_waitcnt lgkmcnt(0)
	v_mfma_f32_16x16x32_bf16 v[60:63], v[138:141], v[176:179], 0
	v_mfma_f32_16x16x32_bf16 v[56:59], v[152:155], v[176:179], 0
	v_mfma_f32_16x16x32_bf16 v[44:47], v[138:141], v[184:187], 0
	v_mfma_f32_16x16x32_bf16 v[40:43], v[152:155], v[184:187], 0
	v_mfma_f32_16x16x32_bf16 v[28:31], v[138:141], v[206:209], 0
	v_mfma_f32_16x16x32_bf16 v[24:27], v[152:155], v[206:209], 0
	v_mfma_f32_16x16x32_bf16 v[12:15], v[138:141], v[214:217], 0
	v_mfma_f32_16x16x32_bf16 v[8:11], v[152:155], v[214:217], 0
	v_mfma_f32_16x16x32_bf16 v[60:63], v[148:151], v[180:183], v[60:63]
	v_mfma_f32_16x16x32_bf16 v[56:59], v[156:159], v[180:183], v[56:59]
	v_mfma_f32_16x16x32_bf16 v[44:47], v[148:151], v[188:191], v[44:47]
	v_mfma_f32_16x16x32_bf16 v[40:43], v[156:159], v[188:191], v[40:43]
	v_mfma_f32_16x16x32_bf16 v[28:31], v[148:151], v[210:213], v[28:31]
	v_mfma_f32_16x16x32_bf16 v[24:27], v[156:159], v[210:213], v[24:27]
	v_mfma_f32_16x16x32_bf16 v[12:15], v[148:151], v[218:221], v[12:15]
	v_mfma_f32_16x16x32_bf16 v[8:11], v[156:159], v[218:221], v[8:11]
	s_setprio 0
	s_setprio 1
	v_mfma_f32_16x16x32_bf16 v[52:55], v[160:163], v[176:179], 0
	v_mfma_f32_16x16x32_bf16 v[48:51], v[168:171], v[176:179], 0
	v_mfma_f32_16x16x32_bf16 v[36:39], v[160:163], v[184:187], 0
	v_mfma_f32_16x16x32_bf16 v[32:35], v[168:171], v[184:187], 0
	v_mfma_f32_16x16x32_bf16 v[20:23], v[160:163], v[206:209], 0
	v_mfma_f32_16x16x32_bf16 v[16:19], v[168:171], v[206:209], 0
	v_mfma_f32_16x16x32_bf16 v[4:7], v[160:163], v[214:217], 0
	v_mfma_f32_16x16x32_bf16 v[0:3], v[168:171], v[214:217], 0
	v_mfma_f32_16x16x32_bf16 v[52:55], v[164:167], v[180:183], v[52:55]
	v_mfma_f32_16x16x32_bf16 v[48:51], v[172:175], v[180:183], v[48:51]
	v_mfma_f32_16x16x32_bf16 v[36:39], v[164:167], v[188:191], v[36:39]
	v_mfma_f32_16x16x32_bf16 v[32:35], v[172:175], v[188:191], v[32:35]
	v_mfma_f32_16x16x32_bf16 v[20:23], v[164:167], v[210:213], v[20:23]
	v_mfma_f32_16x16x32_bf16 v[16:19], v[172:175], v[210:213], v[16:19]
	v_mfma_f32_16x16x32_bf16 v[4:7], v[164:167], v[218:221], v[4:7]
	v_mfma_f32_16x16x32_bf16 v[0:3], v[172:175], v[218:221], v[0:3]
	s_setprio 0
	s_barrier
	s_add_i32 s12, 0, 0x18000
	s_add_i32 s13, 0, 0x1c000
	v_add_u32_e32 v156, s12, v145
	v_add_u32_e32 v172, s13, v145
	ds_read_b128 v[138:141], v156
	ds_read_b128 v[148:151], v156 offset:1024
	ds_read_b128 v[152:155], v156 offset:2048
	ds_read_b128 v[156:159], v156 offset:3072
	ds_read_b128 v[160:163], v172
	ds_read_b128 v[164:167], v172 offset:1024
	ds_read_b128 v[168:171], v172 offset:2048
	ds_read_b128 v[172:175], v172 offset:3072
	s_mov_b32 m0, s9
	s_nop 0
	global_load_lds_dwordx4 v128, s[60:61]
	s_mov_b32 m0, s55
	s_nop 0
	global_load_lds_dwordx4 v130, s[60:61]
	s_add_u32 s10, s60, 0x100000
	s_addc_u32 s11, s61, 0
	s_mov_b32 m0, s62
	ds_read_b128 v[176:179], v147 offset:32768
	ds_read_b128 v[180:183], v147 offset:33792
	ds_read_b128 v[184:187], v147 offset:34816
	ds_read_b128 v[188:191], v147 offset:35840
	ds_read_b128 v[206:209], v147 offset:36864
	ds_read_b128 v[210:213], v147 offset:37888
	ds_read_b128 v[214:217], v147 offset:38912
	ds_read_b128 v[218:221], v147 offset:39936
	global_load_lds_dwordx4 v128, s[10:11]
	s_mov_b32 m0, s63
	s_nop 0
	global_load_lds_dwordx4 v130, s[10:11]
	s_waitcnt vmcnt(8)
	s_waitcnt lgkmcnt(0)
	s_barrier
	s_setprio 1
	s_waitcnt lgkmcnt(0)
	v_mfma_f32_16x16x32_bf16 v[124:127], v[138:141], v[176:179], v[124:127]
	v_mfma_f32_16x16x32_bf16 v[120:123], v[152:155], v[176:179], v[120:123]
	v_mfma_f32_16x16x32_bf16 v[108:111], v[138:141], v[184:187], v[108:111]
	v_mfma_f32_16x16x32_bf16 v[104:107], v[152:155], v[184:187], v[104:107]
	v_mfma_f32_16x16x32_bf16 v[92:95], v[138:141], v[206:209], v[92:95]
	v_mfma_f32_16x16x32_bf16 v[88:91], v[152:155], v[206:209], v[88:91]
	v_mfma_f32_16x16x32_bf16 v[76:79], v[138:141], v[214:217], v[76:79]
	v_mfma_f32_16x16x32_bf16 v[72:75], v[152:155], v[214:217], v[72:75]
	v_mfma_f32_16x16x32_bf16 v[124:127], v[148:151], v[180:183], v[124:127]
	v_mfma_f32_16x16x32_bf16 v[120:123], v[156:159], v[180:183], v[120:123]
	v_mfma_f32_16x16x32_bf16 v[108:111], v[148:151], v[188:191], v[108:111]
	v_mfma_f32_16x16x32_bf16 v[104:107], v[156:159], v[188:191], v[104:107]
	v_mfma_f32_16x16x32_bf16 v[92:95], v[148:151], v[210:213], v[92:95]
	v_mfma_f32_16x16x32_bf16 v[88:91], v[156:159], v[210:213], v[88:91]
	v_mfma_f32_16x16x32_bf16 v[76:79], v[148:151], v[218:221], v[76:79]
	v_mfma_f32_16x16x32_bf16 v[72:75], v[156:159], v[218:221], v[72:75]
	s_setprio 0
	s_setprio 1
	v_mfma_f32_16x16x32_bf16 v[116:119], v[160:163], v[176:179], v[116:119]
	v_mfma_f32_16x16x32_bf16 v[112:115], v[168:171], v[176:179], v[112:115]
	v_mfma_f32_16x16x32_bf16 v[100:103], v[160:163], v[184:187], v[100:103]
	v_mfma_f32_16x16x32_bf16 v[96:99], v[168:171], v[184:187], v[96:99]
	v_mfma_f32_16x16x32_bf16 v[84:87], v[160:163], v[206:209], v[84:87]
	v_mfma_f32_16x16x32_bf16 v[80:83], v[168:171], v[206:209], v[80:83]
	v_mfma_f32_16x16x32_bf16 v[68:71], v[160:163], v[214:217], v[68:71]
	v_mfma_f32_16x16x32_bf16 v[64:67], v[168:171], v[214:217], v[64:67]
	v_mfma_f32_16x16x32_bf16 v[116:119], v[164:167], v[180:183], v[116:119]
	v_mfma_f32_16x16x32_bf16 v[112:115], v[172:175], v[180:183], v[112:115]
	v_mfma_f32_16x16x32_bf16 v[100:103], v[164:167], v[188:191], v[100:103]
	v_mfma_f32_16x16x32_bf16 v[96:99], v[172:175], v[188:191], v[96:99]
	v_mfma_f32_16x16x32_bf16 v[84:87], v[164:167], v[210:213], v[84:87]
	v_mfma_f32_16x16x32_bf16 v[80:83], v[172:175], v[210:213], v[80:83]
	v_mfma_f32_16x16x32_bf16 v[68:71], v[164:167], v[218:221], v[68:71]
	v_mfma_f32_16x16x32_bf16 v[64:67], v[172:175], v[218:221], v[64:67]
	s_setprio 0
	s_barrier
	s_add_i32 s10, s12, s8
	s_add_i32 m0, s10, 0xffffff80
	ds_read_b128 v[176:179], v147 offset:49152
	ds_read_b128 v[180:183], v147 offset:50176
	ds_read_b128 v[184:187], v147 offset:51200
	ds_read_b128 v[188:191], v147 offset:52224
	ds_read_b128 v[206:209], v147 offset:53248
	ds_read_b128 v[210:213], v147 offset:54272
	ds_read_b128 v[214:217], v147 offset:55296
	ds_read_b128 v[218:221], v147 offset:56320
	global_load_lds_dwordx4 v192, s[58:59] offset:128
	s_add_i32 m0, s10, 0x1f80
	s_add_u32 s10, s58, 0x100080
	s_addc_u32 s11, s59, 0
	s_add_i32 s12, s13, s8
	global_load_lds_dwordx4 v132, s[58:59] offset:128
	s_mov_b32 m0, s12
	s_nop 0
	global_load_lds_dwordx4 v192, s[10:11]
	s_add_i32 m0, s12, 0x2000
	s_nop 0
	global_load_lds_dwordx4 v132, s[10:11]
	s_waitcnt vmcnt(6)
	s_waitcnt lgkmcnt(0)
	s_barrier
	s_setprio 1
	s_waitcnt lgkmcnt(0)
	v_mfma_f32_16x16x32_bf16 v[60:63], v[138:141], v[176:179], v[60:63]
	v_mfma_f32_16x16x32_bf16 v[56:59], v[152:155], v[176:179], v[56:59]
	v_mfma_f32_16x16x32_bf16 v[44:47], v[138:141], v[184:187], v[44:47]
	v_mfma_f32_16x16x32_bf16 v[40:43], v[152:155], v[184:187], v[40:43]
	v_mfma_f32_16x16x32_bf16 v[28:31], v[138:141], v[206:209], v[28:31]
	v_mfma_f32_16x16x32_bf16 v[24:27], v[152:155], v[206:209], v[24:27]
	v_mfma_f32_16x16x32_bf16 v[12:15], v[138:141], v[214:217], v[12:15]
	v_mfma_f32_16x16x32_bf16 v[8:11], v[152:155], v[214:217], v[8:11]
	v_mfma_f32_16x16x32_bf16 v[60:63], v[148:151], v[180:183], v[60:63]
	v_mfma_f32_16x16x32_bf16 v[56:59], v[156:159], v[180:183], v[56:59]
	v_mfma_f32_16x16x32_bf16 v[44:47], v[148:151], v[188:191], v[44:47]
	v_mfma_f32_16x16x32_bf16 v[40:43], v[156:159], v[188:191], v[40:43]
	v_mfma_f32_16x16x32_bf16 v[28:31], v[148:151], v[210:213], v[28:31]
	v_mfma_f32_16x16x32_bf16 v[24:27], v[156:159], v[210:213], v[24:27]
	v_mfma_f32_16x16x32_bf16 v[12:15], v[148:151], v[218:221], v[12:15]
	v_mfma_f32_16x16x32_bf16 v[8:11], v[156:159], v[218:221], v[8:11]
	s_setprio 0
	s_setprio 1
	v_mfma_f32_16x16x32_bf16 v[52:55], v[160:163], v[176:179], v[52:55]
	v_mfma_f32_16x16x32_bf16 v[48:51], v[168:171], v[176:179], v[48:51]
	v_mfma_f32_16x16x32_bf16 v[36:39], v[160:163], v[184:187], v[36:39]
	v_mfma_f32_16x16x32_bf16 v[32:35], v[168:171], v[184:187], v[32:35]
	v_mfma_f32_16x16x32_bf16 v[20:23], v[160:163], v[206:209], v[20:23]
	v_mfma_f32_16x16x32_bf16 v[16:19], v[168:171], v[206:209], v[16:19]
	v_mfma_f32_16x16x32_bf16 v[4:7], v[160:163], v[214:217], v[4:7]
	v_mfma_f32_16x16x32_bf16 v[0:3], v[168:171], v[214:217], v[0:3]
	v_mfma_f32_16x16x32_bf16 v[52:55], v[164:167], v[180:183], v[52:55]
	v_mfma_f32_16x16x32_bf16 v[48:51], v[172:175], v[180:183], v[48:51]
	v_mfma_f32_16x16x32_bf16 v[36:39], v[164:167], v[188:191], v[36:39]
	v_mfma_f32_16x16x32_bf16 v[32:35], v[172:175], v[188:191], v[32:35]
	v_mfma_f32_16x16x32_bf16 v[20:23], v[164:167], v[210:213], v[20:23]
	v_mfma_f32_16x16x32_bf16 v[16:19], v[172:175], v[210:213], v[16:19]
	v_mfma_f32_16x16x32_bf16 v[4:7], v[164:167], v[218:221], v[4:7]
	v_mfma_f32_16x16x32_bf16 v[0:3], v[172:175], v[218:221], v[0:3]
	s_setprio 0
	s_barrier
	s_add_i32 s83, s83, 2
	s_add_u32 s56, s56, 0x100
	s_addc_u32 s57, s57, 0
	s_add_u32 s79, s79, 0x100
	s_addc_u32 s82, s82, 0
	s_cmp_gt_u32 s83, 61
